# scan task prologue: the two dead D*u operand loads removed (on top of the ds_write2 version)
# baseline (speedup 1.0000x reference)
.LBB0_563:
	s_and_b32 s13, s6, 0xff
	s_lshl_b32 s0, s13, 2
	v_mov_b32_e32 v0, s0
	global_load_dword v2, v0, s[38:39]
	s_lshl_b32 s4, s13, 6
	v_or_b32_e32 v0, s4, v174
	v_lshlrev_b32_e32 v3, 2, v0
	global_load_dword v21, v3, s[58:59]
	global_load_dword v20, v3, s[36:37]
	s_and_b32 s2, s10, 0x1800
	v_or_b32_e32 v1, s2, v182
	v_lshlrev_b32_e32 v1, 3, v1
	s_bfe_u32 s0, s12, 0x70001
	v_and_b32_e32 v1, 0xc180, v1
	v_or_b32_e32 v1, s0, v1
	v_lshlrev_b32_e32 v132, 10, v1
	v_lshl_add_u64 v[150:151], v[144:145], 0, v[132:133]
	v_lshl_add_u64 v[152:153], v[146:147], 0, v[132:133]
	v_lshl_add_u64 v[154:155], v[148:149], 0, v[132:133]
	v_lshlrev_b32_e32 v132, 6, v0
	v_lshl_add_u64 v[0:1], v[136:137], 0, v[132:133]
	global_load_dwordx4 v[4:7], v[0:1], off
	global_load_dwordx4 v[8:11], v[0:1], off offset:16
	v_lshl_add_u64 v[0:1], v[134:135], 0, v[132:133]
	global_load_dwordx4 v[12:15], v[0:1], off
	global_load_dwordx4 v[16:19], v[0:1], off offset:16
	v_or_b32_e32 v0, s4, v173
	v_lshlrev_b32_e32 v22, 2, v0
	v_or_b32_e32 v132, 0x800, v132
	s_bfe_u32 s16, s6, 0x70001
	v_mov_b32_e32 v188, 0
	v_mov_b32_e32 v189, v133
	s_waitcnt vmcnt(6)
	v_mul_f32_e32 v0, 0x3fb8aa3b, v2
	v_exp_f32_e32 v0, v0
	global_load_dword v2, v22, s[58:59]
	global_load_dword v1, v22, s[36:37]
	s_waitcnt vmcnt(7)
	v_mov_b32_e32 v22, v21
	v_mov_b32_e32 v25, v21
	v_mul_f32_e32 v23, v0, v21
	s_waitcnt vmcnt(6)
	v_mul_f32_e32 v24, v0, v20
	v_mul_f32_e32 v23, 0x3fb8aa3b, v23
	v_mul_f32_e32 v24, 0.15915494, v24
	v_exp_f32_e32 v23, v23
	v_sin_f32_e32 v26, v24
	v_cos_f32_e32 v24, v24
	v_mov_b32_e32 v27, v20
	v_mul_f32_e32 v28, v23, v26
	v_fma_f32 v29, v23, v24, -1.0
	v_mov_b32_e32 v24, v28
	v_mov_b32_e32 v26, v29
	v_pk_mul_f32 v[30:31], v[20:21], v[28:29]
	v_pk_mul_f32 v[22:23], v[22:23], v[24:25] op_sel_hi:[0,1]
	v_pk_mul_f32 v[20:21], v[20:21], v[26:27] op_sel_hi:[0,1]
	v_add_f32_e32 v28, v30, v31
	v_add_f32_e32 v21, v23, v21
	v_sub_f32_e32 v22, v22, v20
	v_div_scale_f32 v20, s[0:1], v21, v21, v28
	v_div_scale_f32 v24, s[0:1], v21, v21, v22
	v_rcp_f32_e32 v25, v20
	v_rcp_f32_e32 v26, v24
	v_div_scale_f32 v23, vcc, v28, v21, v28
	v_fma_f32 v29, -v20, v25, 1.0
	v_fma_f32 v30, -v24, v26, 1.0
	v_fmac_f32_e32 v25, v29, v25
	v_div_scale_f32 v27, s[0:1], v22, v21, v22
	v_fmac_f32_e32 v26, v30, v26
	v_mul_f32_e32 v29, v23, v25
	v_mul_f32_e32 v30, v27, v26
	v_fma_f32 v31, -v20, v29, v23
	v_fma_f32 v32, -v24, v30, v27
	v_fmac_f32_e32 v29, v31, v25
	v_fmac_f32_e32 v30, v32, v26
	v_fma_f32 v20, -v20, v29, v23
	v_fma_f32 v23, -v24, v30, v27
	v_div_fmas_f32 v20, v20, v25, v29
	s_mov_b64 vcc, s[0:1]
	v_div_fmas_f32 v23, v23, v26, v30
	v_div_fixup_f32 v22, v23, v21, v22
	v_div_fixup_f32 v20, v20, v21, v28
	s_waitcnt vmcnt(5)
	v_pk_mul_f32 v[24:25], v[4:5], v[22:23] op_sel_hi:[1,0]
	v_pk_mul_f32 v[26:27], v[6:7], v[22:23] op_sel_hi:[1,0]
	s_waitcnt vmcnt(4)
	v_pk_mul_f32 v[28:29], v[8:9], v[22:23] op_sel_hi:[1,0]
	v_pk_mul_f32 v[30:31], v[10:11], v[22:23] op_sel_hi:[1,0]
	s_waitcnt vmcnt(3)
	v_pk_mul_f32 v[32:33], v[12:13], v[22:23] op_sel_hi:[1,0]
	v_pk_mul_f32 v[34:35], v[14:15], v[22:23] op_sel_hi:[1,0]
	s_waitcnt vmcnt(2)
	v_pk_mul_f32 v[36:37], v[16:17], v[22:23] op_sel_hi:[1,0]
	v_pk_mul_f32 v[22:23], v[18:19], v[22:23] op_sel_hi:[1,0]
	v_pk_fma_f32 v[14:15], v[14:15], v[20:21], v[26:27] op_sel_hi:[1,0,1] neg_lo:[0,0,1] neg_hi:[0,0,1]
	v_pk_fma_f32 v[12:13], v[12:13], v[20:21], v[24:25] op_sel_hi:[1,0,1] neg_lo:[0,0,1] neg_hi:[0,0,1]
	v_pk_fma_f32 v[18:19], v[18:19], v[20:21], v[30:31] op_sel_hi:[1,0,1] neg_lo:[0,0,1] neg_hi:[0,0,1]
	v_pk_fma_f32 v[16:17], v[16:17], v[20:21], v[28:29] op_sel_hi:[1,0,1] neg_lo:[0,0,1] neg_hi:[0,0,1]
	v_pk_fma_f32 v[6:7], v[6:7], v[20:21], v[34:35] op_sel_hi:[1,0,1]
	v_pk_fma_f32 v[4:5], v[4:5], v[20:21], v[32:33] op_sel_hi:[1,0,1]
	v_pk_fma_f32 v[10:11], v[10:11], v[20:21], v[22:23] op_sel_hi:[1,0,1]
	v_pk_fma_f32 v[8:9], v[8:9], v[20:21], v[36:37] op_sel_hi:[1,0,1]
	v_cvt_pk_bf16_f32 v104, v12, v13
	v_cvt_pk_bf16_f32 v105, v14, v15
	v_cvt_pk_bf16_f32 v106, v16, v17
	v_cvt_pk_bf16_f32 v107, v18, v19
	v_cvt_pk_bf16_f32 v92, v4, v5
	v_cvt_pk_bf16_f32 v93, v6, v7
	s_nop 0
	v_cvt_pk_bf16_f32 v94, v8, v9
	v_cvt_pk_bf16_f32 v95, v10, v11
	v_lshl_or_b32 v58, s13, 12, v183
	v_mov_b32_e32 v59, 0
	v_lshl_add_u64 v[60:61], v[138:139], 0, v[58:59]
	v_lshl_add_u64 v[62:63], v[140:141], 0, v[58:59]
	global_load_dwordx4 v[196:199], v[60:61], off
	global_load_dwordx4 v[200:203], v[62:63], off
	global_load_dwordx4 v[204:207], v[60:61], off offset:32
	global_load_dwordx4 v[208:211], v[62:63], off offset:32
	global_load_dwordx4 v[212:215], v[60:61], off offset:64
	global_load_dwordx4 v[216:219], v[62:63], off offset:64
	global_load_dwordx4 v[220:223], v[60:61], off offset:96
	global_load_dwordx4 v[224:227], v[62:63], off offset:96
	global_load_dwordx4 v[228:231], v[60:61], off offset:128
	global_load_dwordx4 v[232:235], v[62:63], off offset:128
	global_load_dwordx4 v[236:239], v[60:61], off offset:160
	global_load_dwordx4 v[240:243], v[62:63], off offset:160
	global_load_dwordx4 v[244:247], v[60:61], off offset:192
	global_load_dwordx4 v[40:43], v[62:63], off offset:192
	global_load_dwordx4 v[44:47], v[60:61], off offset:224
	global_load_dwordx4 v[48:51], v[62:63], off offset:224
	global_load_dword v21, v3, s[58:59] offset:128
	global_load_dword v20, v3, s[36:37] offset:128
	v_lshl_add_u64 v[12:13], v[136:137], 0, v[132:133]
	v_lshl_add_u64 v[22:23], v[134:135], 0, v[132:133]
	global_load_dwordx4 v[4:7], v[12:13], off
	global_load_dwordx4 v[8:11], v[12:13], off offset:16
	s_nop 0
	global_load_dwordx4 v[12:15], v[22:23], off
	global_load_dwordx4 v[16:19], v[22:23], off offset:16
	v_lshl_or_b32 v132, s13, 12, v183
	v_lshl_add_u64 v[22:23], v[138:139], 0, v[132:133]
	s_waitcnt vmcnt(7)
	v_mul_f32_e32 v2, v2, v0
	v_mul_f32_e32 v2, 0x3fb8aa3b, v2
	v_exp_f32_e32 v2, v2
	s_waitcnt vmcnt(5)
	v_mul_f32_e32 v3, v0, v21
	s_waitcnt vmcnt(4)
	v_mul_f32_e32 v25, v0, v20
	v_mul_f32_e32 v3, 0x3fb8aa3b, v3
	v_mul_f32_e32 v25, 0.15915494, v25
	v_exp_f32_e32 v3, v3
	v_sin_f32_e32 v26, v25
	v_cos_f32_e32 v25, v25
	v_mov_b32_e32 v24, v21
	v_mov_b32_e32 v27, v21
	v_mul_f32_e32 v30, v3, v26
	v_fma_f32 v31, v3, v25, -1.0
	v_mov_b32_e32 v29, v20
	v_mov_b32_e32 v26, v30
	v_mov_b32_e32 v28, v31
	v_pk_mul_f32 v[32:33], v[20:21], v[30:31]
	v_pk_mul_f32 v[24:25], v[24:25], v[26:27] op_sel_hi:[0,1]
	v_pk_mul_f32 v[20:21], v[20:21], v[28:29] op_sel_hi:[0,1]
	v_add_f32_e32 v3, v32, v33
	v_add_f32_e32 v21, v25, v21
	v_sub_f32_e32 v24, v24, v20
	v_div_scale_f32 v20, s[0:1], v21, v21, v3
	v_div_scale_f32 v26, s[0:1], v21, v21, v24
	v_rcp_f32_e32 v27, v20
	v_rcp_f32_e32 v28, v26
	v_div_scale_f32 v25, vcc, v3, v21, v3
	v_fma_f32 v30, -v20, v27, 1.0
	v_fma_f32 v31, -v26, v28, 1.0
	v_fmac_f32_e32 v27, v30, v27
	v_div_scale_f32 v29, s[0:1], v24, v21, v24
	v_fmac_f32_e32 v28, v31, v28
	v_mul_f32_e32 v30, v25, v27
	v_mul_f32_e32 v31, v29, v28
	v_fma_f32 v32, -v20, v30, v25
	v_fma_f32 v33, -v26, v31, v29
	v_fmac_f32_e32 v30, v32, v27
	v_fmac_f32_e32 v31, v33, v28
	v_fma_f32 v20, -v20, v30, v25
	v_fma_f32 v25, -v26, v31, v29
	v_div_fmas_f32 v20, v20, v27, v30
	s_mov_b64 vcc, s[0:1]
	v_div_fixup_f32 v20, v20, v21, v3
	v_div_fmas_f32 v3, v25, v28, v31
	v_div_fixup_f32 v24, v3, v21, v24
	s_waitcnt vmcnt(3)
	v_pk_mul_f32 v[26:27], v[4:5], v[24:25] op_sel_hi:[1,0]
	v_pk_mul_f32 v[28:29], v[6:7], v[24:25] op_sel_hi:[1,0]
	s_waitcnt vmcnt(2)
	v_pk_mul_f32 v[30:31], v[8:9], v[24:25] op_sel_hi:[1,0]
	v_pk_mul_f32 v[32:33], v[10:11], v[24:25] op_sel_hi:[1,0]
	s_waitcnt vmcnt(1)
	v_pk_mul_f32 v[34:35], v[12:13], v[24:25] op_sel_hi:[1,0]
	v_pk_mul_f32 v[36:37], v[14:15], v[24:25] op_sel_hi:[1,0]
	s_waitcnt vmcnt(0)
	v_pk_mul_f32 v[38:39], v[16:17], v[24:25] op_sel_hi:[1,0]
	v_pk_mul_f32 v[24:25], v[18:19], v[24:25] op_sel_hi:[1,0]
	v_pk_fma_f32 v[12:13], v[12:13], v[20:21], v[26:27] op_sel_hi:[1,0,1] neg_lo:[0,0,1] neg_hi:[0,0,1]
	v_pk_fma_f32 v[6:7], v[6:7], v[20:21], v[36:37] op_sel_hi:[1,0,1]
	v_pk_fma_f32 v[4:5], v[4:5], v[20:21], v[34:35] op_sel_hi:[1,0,1]
	v_pk_fma_f32 v[10:11], v[10:11], v[20:21], v[24:25] op_sel_hi:[1,0,1]
	v_pk_fma_f32 v[8:9], v[8:9], v[20:21], v[38:39] op_sel_hi:[1,0,1]
	v_cvt_pk_bf16_f32 v116, v12, v13
	v_lshl_add_u64 v[12:13], v[140:141], 0, v[132:133]
	v_pk_fma_f32 v[14:15], v[14:15], v[20:21], v[28:29] op_sel_hi:[1,0,1] neg_lo:[0,0,1] neg_hi:[0,0,1]
	v_pk_fma_f32 v[18:19], v[18:19], v[20:21], v[32:33] op_sel_hi:[1,0,1] neg_lo:[0,0,1] neg_hi:[0,0,1]
	v_pk_fma_f32 v[16:17], v[16:17], v[20:21], v[30:31] op_sel_hi:[1,0,1] neg_lo:[0,0,1] neg_hi:[0,0,1]
	v_cvt_pk_bf16_f32 v117, v14, v15
	s_lshl_b32 s1, s6, 3
	v_cvt_pk_bf16_f32 v118, v16, v17
	v_cvt_pk_bf16_f32 v119, v18, v19
	v_cvt_pk_bf16_f32 v112, v4, v5
	v_cvt_pk_bf16_f32 v113, v6, v7
	v_cvt_pk_bf16_f32 v114, v8, v9
	v_cvt_pk_bf16_f32 v115, v10, v11
	s_and_b32 s15, s1, 0x1800
	v_or_b32_e32 v3, s15, v174
	v_lshlrev_b32_e32 v3, 3, v3
	s_lshl_b32 s0, s6, 4
	v_and_b32_e32 v3, 0xc080, v3
	s_and_b32 s14, s0, 16
	v_or_b32_e32 v3, s16, v3
	v_or_b32_e32 v132, s14, v176
	v_lshl_or_b32 v3, v3, 9, v177
	v_or3_b32 v14, s14, v175, v3
	v_or_b32_e32 v3, v3, v132
	v_lshlrev_b32_e32 v3, 1, v3
	v_lshlrev_b32_e32 v14, 1, v14
	v_or_b32_e32 v15, 16, v3
	v_mul_f32_e32 v0, v0, v1
	v_mul_f32_e32 v1, 0.15915494, v0
	v_cos_f32_e32 v0, v1
	v_sin_f32_e32 v1, v1
	s_mov_b64 s[0:1], 0
	s_mov_b32 s16, 0
	v_pk_mul_f32 v[198:199], v[126:127], v[198:199]
	v_pk_mul_f32 v[196:197], v[124:125], v[196:197]
	v_pk_mul_f32 v[202:203], v[130:131], v[202:203]
	v_pk_mul_f32 v[200:201], v[128:129], v[200:201]
	s_nop 0
	v_cvt_pk_bf16_f32 v64, v196, v200
	v_cvt_pk_bf16_f32 v65, v197, v201
	v_cvt_pk_bf16_f32 v66, v198, v202
	v_cvt_pk_bf16_f32 v67, v199, v203
	v_pk_mul_f32 v[206:207], v[126:127], v[206:207]
	v_pk_mul_f32 v[204:205], v[124:125], v[204:205]
	v_pk_mul_f32 v[210:211], v[130:131], v[210:211]
	v_pk_mul_f32 v[208:209], v[128:129], v[208:209]
	s_nop 0
	v_cvt_pk_bf16_f32 v68, v204, v208
	v_cvt_pk_bf16_f32 v69, v205, v209
	v_cvt_pk_bf16_f32 v70, v206, v210
	v_cvt_pk_bf16_f32 v71, v207, v211
	v_pk_mul_f32 v[214:215], v[126:127], v[214:215]
	v_pk_mul_f32 v[212:213], v[124:125], v[212:213]
	v_pk_mul_f32 v[218:219], v[130:131], v[218:219]
	v_pk_mul_f32 v[216:217], v[128:129], v[216:217]
	s_nop 0
	v_cvt_pk_bf16_f32 v72, v212, v216
	v_cvt_pk_bf16_f32 v73, v213, v217
	v_cvt_pk_bf16_f32 v74, v214, v218
	v_cvt_pk_bf16_f32 v75, v215, v219
	v_pk_mul_f32 v[222:223], v[126:127], v[222:223]
	v_pk_mul_f32 v[220:221], v[124:125], v[220:221]
	v_pk_mul_f32 v[226:227], v[130:131], v[226:227]
	v_pk_mul_f32 v[224:225], v[128:129], v[224:225]
	s_nop 0
	v_cvt_pk_bf16_f32 v76, v220, v224
	v_cvt_pk_bf16_f32 v77, v221, v225
	v_cvt_pk_bf16_f32 v78, v222, v226
	v_cvt_pk_bf16_f32 v79, v223, v227
	v_pk_mul_f32 v[230:231], v[126:127], v[230:231]
	v_pk_mul_f32 v[228:229], v[124:125], v[228:229]
	v_pk_mul_f32 v[234:235], v[130:131], v[234:235]
	v_pk_mul_f32 v[232:233], v[128:129], v[232:233]
	s_nop 0
	v_cvt_pk_bf16_f32 v84, v228, v232
	v_cvt_pk_bf16_f32 v85, v229, v233
	v_cvt_pk_bf16_f32 v86, v230, v234
	v_cvt_pk_bf16_f32 v87, v231, v235
	v_pk_mul_f32 v[238:239], v[126:127], v[238:239]
	v_pk_mul_f32 v[236:237], v[124:125], v[236:237]
	v_pk_mul_f32 v[242:243], v[130:131], v[242:243]
	v_pk_mul_f32 v[240:241], v[128:129], v[240:241]
	s_nop 0
	v_cvt_pk_bf16_f32 v88, v236, v240
	v_cvt_pk_bf16_f32 v89, v237, v241
	v_cvt_pk_bf16_f32 v90, v238, v242
	v_cvt_pk_bf16_f32 v91, v239, v243
	v_pk_mul_f32 v[246:247], v[126:127], v[246:247]
	v_pk_mul_f32 v[244:245], v[124:125], v[244:245]
	v_pk_mul_f32 v[42:43], v[130:131], v[42:43]
	v_pk_mul_f32 v[40:41], v[128:129], v[40:41]
	s_nop 0
	v_cvt_pk_bf16_f32 v96, v244, v40
	v_cvt_pk_bf16_f32 v97, v245, v41
	v_cvt_pk_bf16_f32 v98, v246, v42
	v_cvt_pk_bf16_f32 v99, v247, v43
	v_lshl_add_u64 v[12:13], v[142:143], 0, s[4:5]
	s_bfe_u32 s4, s6, 0x10001
	v_pk_mul_f32 v[46:47], v[126:127], v[46:47]
	v_pk_mul_f32 v[44:45], v[124:125], v[44:45]
	v_pk_mul_f32 v[50:51], v[130:131], v[50:51]
	v_pk_mul_f32 v[48:49], v[128:129], v[48:49]
	s_nop 0
	v_cvt_pk_bf16_f32 v108, v44, v48
	v_cvt_pk_bf16_f32 v109, v45, v49
	v_cvt_pk_bf16_f32 v110, v46, v50
	v_cvt_pk_bf16_f32 v111, v47, v51
	global_load_dwordx4 v[100:103], v[12:13], off
	global_load_dwordx4 v[80:83], v[12:13], off offset:32
	global_load_dwordx4 v[120:123], v14, s[54:55]
	v_or_b32_e32 v3, s2, v174
	v_pk_mul_f32 v[160:161], v[0:1], v[2:3] op_sel_hi:[1,0]
	v_lshrrev_b32_e32 v187, 3, v3
	v_pk_mov_b32 v[162:163], v[160:161], v[160:161] op_sel:[1,0]
	v_mov_b32_e32 v164, v160
	v_mov_b32_e32 v165, v160
	v_mov_b32_e32 v166, v161
	v_mov_b32_e32 v167, v161
	v_mov_b32_e32 v184, 0xbdd2d3e8
	global_load_dwordx4 v[168:171], v[152:153], off
	s_add_u32 s0, s0, 0x40000
	s_addc_u32 s1, s1, 0
	v_lshl_add_u64 v[216:217], v[152:153], 0, s[0:1]
	global_load_dwordx4 v[156:159], v[216:217], off
	s_add_u32 s0, s0, 0x40000
	s_addc_u32 s1, s1, 0
	v_lshl_add_u64 v[216:217], v[152:153], 0, s[0:1]
	global_load_dwordx4 v[178:181], v[216:217], off
	s_and_b32 s18, s16, 0x2000
	s_and_b32 s17, s2, 0x1f00
	s_or_b32 s17, s17, s13
	s_lshl_b32 s17, s17, 12
	s_and_b32 s17, s17, 0x1ffc000
	v_add_u32_e32 v222, s2, v174
	v_and_or_b32 v223, v187, 14, s4
	v_lshlrev_b32_e32 v225, 5, v222
	v_lshlrev_b32_e32 v226, 1, v222
	v_lshl_or_b32 v227, v223, 9, s18
	v_and_b32_e32 v222, 0x1e0, v225
	v_and_b32_e32 v223, 16, v226
	v_or_b32_e32 v224, v222, v132
	v_bitop3_b32 v222, v222, v223, v132 bitop3:0x36
	v_or_b32_e32 v225, s17, v227
	v_bitop3_b32 v226, v224, v223, 8 bitop3:0x36
	v_or_b32_e32 v227, v222, v225
	v_or_b32_e32 v254, v226, v225
	v_lshlrev_b32_e32 v253, 1, v227
	v_lshlrev_b32_e32 v254, 1, v254
	s_mov_b64 s[14:15], s[90:91]
	v_add_u32_e32 v222, 18432, v185
	v_add_u32_e32 v223, 19520, v185
	v_add_u32_e32 v224, 20608, v185
	v_add_u32_e32 v225, 21696, v185
	v_add_u32_e32 v226, 22784, v185
	v_add_u32_e32 v227, 23872, v185
	v_add_u32_e32 v190, 24960, v185
	v_add_u32_e32 v191, 26048, v185
	s_branch .Lscan_tile
